# P0: w_in transposes 5 items per wave on the 192 GEMV workgroups, 9 on the other 64
# speedup vs baseline: 1.0032x; 1.0012x over previous
; __device__ __forceinline__ int lane_id() { int l; asm volatile("v_mbcnt_lo_u32_b32 %0, -1, 0\n\tv_mbcnt_hi_u32_b32 %0, -1, %0" : "=v"(l)); return l; }
; #define LAS __attribute__((address_space(3)))
; template <bool QKPERM, bool BIAS>
; __device__ __forceinline__ void transpose_item(const float* W, int K, int N, bf16* WT, int row_off, LAS float* scr, int item, int lane, const float* sh2 = nullptr, float* bias2 = nullptr) {
;     const int nblk = N / 32, kb = item / nblk, nb = item % nblk, k0 = 64 * kb, n0 = 32 * nb;
;     if (BIAS) row_off += (n0 >> 7) * 128;
;     float wv[32];
; #pragma unroll
;     for (int i = 0; i < 32; ++i) wv[i] = __builtin_nontemporal_load(W + (size_t)(k0 + 2 * i + (lane >> 5)) * N + n0 + (lane & 31));
; __device__ __forceinline__ void phase_wconv_in(const Params& p, LAS unsigned char* lds, int gw, int NGW) {
;     const int lane = lane_id(), wave = p.wave_id;
;     LAS float* scr = (LAS float*)(lds + wave * 16384);
;     constexpr int I_IN = (D_MODEL / 64) * (IN_COLS / 32);
;     for (int it = gw; it < I_IN; it += NGW) transpose_item<true, false>(p.w_in, D_MODEL, IN_COLS, (bf16*)(p.ws + WS_WINT), 0, scr, it, lane);
; }
.LBB0_43:
	s_lshr_b32 s3, s3, 6
	s_lshl_b32 s4, s74, 3
	s_add_i32 s48, s4, s3
	s_lshl_b32 s46, s33, 3
	s_cmpk_lg_i32 s33, 0x100
	s_cbranch_scc1 .Lwin_std
	s_cmpk_lt_i32 s74, 0xc0
	s_cbranch_scc1 .Lwin_a
	s_add_i32 s96, s48, 0x1800
	s_movk_i32 s97, 0x200
	s_movk_i32 s98, 0x3000
	s_branch .Lwin_set
.Lwin_a:
	s_mov_b32 s96, s48
	s_movk_i32 s97, 0x600
	s_movk_i32 s98, 0x1e00
	s_branch .Lwin_set
.Lwin_std:
	s_mov_b32 s96, s48
	s_mov_b32 s97, s46
	s_movk_i32 s98, 0x3000
.Lwin_set:
	s_cmp_ge_i32 s96, s98
	s_barrier
	v_mbcnt_lo_u32_b32 v0, -1, 0
	v_mbcnt_hi_u32_b32 v0, -1, v0
	s_cbranch_scc1 .LBB0_46
	v_ashrrev_i32_e32 v4, 5, v0
	v_lshlrev_b32_e32 v1, 2, v0
	v_ashrrev_i32_e32 v5, 3, v0
	v_lshlrev_b32_e32 v0, 3, v0
	s_lshl_b32 s4, s3, 14
	v_and_b32_e32 v13, 56, v0
	s_add_i32 s4, s4, 0
	v_and_b32_e32 v2, 0x7c, v1
	v_mul_u32_u24_e32 v0, 0x84, v13
	v_lshlrev_b32_e32 v1, 2, v5
	v_add3_u32 v6, s4, v0, v1
	v_lshlrev_b32_e32 v0, 1, v5
	v_add_u32_e32 v1, 16, v0
	s_movk_i32 s5, 0x84
	v_and_b32_e32 v7, 32, v0
	v_and_b32_e32 v8, 32, v1
	v_add_u32_e32 v1, 32, v0
	v_add_u32_e32 v0, 48, v0
	v_mov_b32_e32 v3, 0
	v_add_u32_e32 v11, s4, v2
	v_mul_lo_u32 v12, v4, s5
	v_and_b32_e32 v9, 32, v1
	v_and_b32_e32 v10, 32, v0
	v_lshl_add_u64 v[0:1], s[14:15], 0, v[2:3]
	v_lshlrev_b32_e32 v2, 1, v13
	v_lshl_add_u64 v[2:3], s[20:21], 0, v[2:3]
	s_mov_b64 s[4:5], 0x14342000
	v_add_u32_e32 v11, v11, v12
	v_lshl_add_u64 v[2:3], v[2:3], 0, s[4:5]
	s_lshl_b32 s8, s96, 5
	s_lshl_b32 s9, s97, 5
	s_mov_b32 s10, 0xc000
	s_movk_i32 s11, 0x800
	v_add_u32_e32 v12, 0x400, v11
	v_add_u32_e32 v13, 0x800, v11
	v_add_u32_e32 v14, 0xc00, v11
	v_add_u32_e32 v15, 0x1000, v11
	v_add_u32_e32 v16, 0x1400, v11
	v_add_u32_e32 v17, 0x1800, v11
	v_add_u32_e32 v18, 0x1c00, v11
	s_mov_b32 s12, s96
.LBB0_45:
	s_mul_hi_i32 s4, s12, 0x2aaaaaab
	s_lshr_b32 s5, s4, 31
	s_ashr_i32 s4, s4, 6
	s_add_i32 s5, s4, s5
	s_lshl_b32 s4, s5, 6
	s_mulk_i32 s5, 0xd000
	s_add_i32 s6, s8, s5
	v_add_u32_e32 v19, s4, v4
	s_ashr_i32 s7, s6, 31
	s_ashr_i32 s5, s4, 31
	v_add_u32_e32 v30, 6, v19
	v_add_u32_e32 v32, 8, v19
	v_add_u32_e32 v34, 10, v19
	v_add_u32_e32 v44, 20, v19
	v_add_u32_e32 v46, 22, v19
	v_add_u32_e32 v48, 24, v19
	v_add_u32_e32 v50, 26, v19
	v_add_u32_e32 v52, 28, v19
	v_add_u32_e32 v54, 30, v19
	v_lshl_add_u64 v[22:23], s[6:7], 2, v[0:1]
	v_add_u32_e32 v26, 2, v19
	v_add_u32_e32 v28, 4, v19
	v_add_u32_e32 v36, 12, v19
	v_add_u32_e32 v38, 14, v19
	v_add_u32_e32 v40, 16, v19
	v_add_u32_e32 v42, 18, v19
	v_add_u32_e32 v56, 32, v19
	v_add_u32_e32 v58, 34, v19
	v_add_u32_e32 v60, 36, v19
	v_add_u32_e32 v62, 38, v19
	v_add_u32_e32 v64, 40, v19
	v_add_u32_e32 v66, 42, v19
	v_add_u32_e32 v68, 44, v19
	v_add_u32_e32 v70, 46, v19
	v_add_u32_e32 v72, 48, v19
	v_add_u32_e32 v74, 50, v19
	v_add_u32_e32 v76, 52, v19
	v_add_u32_e32 v78, 54, v19
	v_add_u32_e32 v80, 56, v19
	v_add_u32_e32 v82, 58, v19
	v_add_u32_e32 v84, 60, v19
	v_add_u32_e32 v86, 62, v19
	v_lshl_add_u64 v[20:21], s[4:5], 1, v[2:3]
	v_mad_i64_i32 v[24:25], s[4:5], v19, s10, v[22:23]
	v_mad_i64_i32 v[30:31], s[4:5], v30, s10, v[22:23]
	v_mad_i64_i32 v[32:33], s[4:5], v32, s10, v[22:23]
	v_mad_i64_i32 v[34:35], s[4:5], v34, s10, v[22:23]
	v_mad_i64_i32 v[44:45], s[4:5], v44, s10, v[22:23]
	v_mad_i64_i32 v[46:47], s[4:5], v46, s10, v[22:23]
	v_mad_i64_i32 v[48:49], s[4:5], v48, s10, v[22:23]
	v_mad_i64_i32 v[50:51], s[4:5], v50, s10, v[22:23]
	v_mad_i64_i32 v[52:53], s[4:5], v52, s10, v[22:23]
	v_mad_i64_i32 v[54:55], s[4:5], v54, s10, v[22:23]
	v_mad_i64_i32 v[26:27], s[4:5], v26, s10, v[22:23]
	v_mad_i64_i32 v[28:29], s[4:5], v28, s10, v[22:23]
	v_mad_i64_i32 v[36:37], s[4:5], v36, s10, v[22:23]
	v_mad_i64_i32 v[38:39], s[4:5], v38, s10, v[22:23]
	v_mad_i64_i32 v[40:41], s[4:5], v40, s10, v[22:23]
	v_mad_i64_i32 v[42:43], s[4:5], v42, s10, v[22:23]
	v_mad_i64_i32 v[56:57], s[4:5], v56, s10, v[22:23]
	v_mad_i64_i32 v[58:59], s[4:5], v58, s10, v[22:23]
	v_mad_i64_i32 v[60:61], s[4:5], v60, s10, v[22:23]
	v_mad_i64_i32 v[62:63], s[4:5], v62, s10, v[22:23]
	v_mad_i64_i32 v[64:65], s[4:5], v64, s10, v[22:23]
	v_mad_i64_i32 v[66:67], s[4:5], v66, s10, v[22:23]
	v_mad_i64_i32 v[68:69], s[4:5], v68, s10, v[22:23]
	v_mad_i64_i32 v[70:71], s[4:5], v70, s10, v[22:23]
	v_mad_i64_i32 v[72:73], s[4:5], v72, s10, v[22:23]
	v_mad_i64_i32 v[74:75], s[4:5], v74, s10, v[22:23]
	v_mad_i64_i32 v[76:77], s[4:5], v76, s10, v[22:23]
	v_mad_i64_i32 v[78:79], s[4:5], v78, s10, v[22:23]
	v_mad_i64_i32 v[80:81], s[4:5], v80, s10, v[22:23]
	v_mad_i64_i32 v[82:83], s[4:5], v82, s10, v[22:23]
	v_mad_i64_i32 v[84:85], s[4:5], v84, s10, v[22:23]
	v_mad_i64_i32 v[22:23], s[4:5], v86, s10, v[22:23]
	global_load_dword v19, v[24:25], off nt
	global_load_dword v86, v[26:27], off nt
	global_load_dword v96, v[28:29], off nt
	global_load_dword v97, v[30:31], off nt
	global_load_dword v98, v[32:33], off nt
	global_load_dword v99, v[34:35], off nt
	global_load_dword v100, v[36:37], off nt
	global_load_dword v101, v[38:39], off nt
	global_load_dword v102, v[40:41], off nt
	global_load_dword v103, v[42:43], off nt
	global_load_dword v104, v[44:45], off nt
	global_load_dword v105, v[46:47], off nt
	global_load_dword v106, v[48:49], off nt
	global_load_dword v107, v[50:51], off nt
; #define LAS __attribute__((address_space(3)))
; __device__ __forceinline__ unsigned pk2(float lo, float hi) { const f32x2_t v = {lo, hi}; const bf16x2_t b = __builtin_convertvector(v, bf16x2_t); return __builtin_bit_cast(unsigned, b); }
; template <bool QKPERM, bool BIAS>
; __device__ __forceinline__ void transpose_item(const float* W, int K, int N, bf16* WT, int row_off, LAS float* scr, int item, int lane, const float* sh2 = nullptr, float* bias2 = nullptr) {
;     ...
;     for (int i = 0; i < 32; ++i) wv[i] = __builtin_nontemporal_load(W + (size_t)(k0 + 2 * i + (lane >> 5)) * N + n0 + (lane & 31));
; #pragma unroll
;     for (int i = 0; i < 32; ++i) scr[(2 * i + (lane >> 5)) * 33 + (lane & 31)] = wv[i];
;     if (BIAS) {
;         float a0 = 0.f, a1 = 0.f, a2 = 0.f, a3 = 0.f;
; #pragma unroll
;         for (int i = 0; i < 32; ++i) { const int k = k0 + 2 * i + (lane >> 5); const float w = wv[i];
;             a0 += w * sh2[0 * IN_COLS + k]; a1 += w * sh2[1 * IN_COLS + k]; a2 += w * sh2[2 * IN_COLS + k]; a3 += w * sh2[3 * IN_COLS + k]; }
;         a0 = half_swap_sum(a0); a1 = half_swap_sum(a1); a2 = half_swap_sum(a2); a3 = half_swap_sum(a3);
;         if (lane < 32) { float* bp = bias2 + row_off + n0 + lane; atomicAdd(bp, a0); atomicAdd(bp + 2 * FFN, a1); atomicAdd(bp + 4 * FFN, a2); atomicAdd(bp + 6 * FFN, a3); }
;     }
;     asm volatile("s_waitcnt lgkmcnt(0)" ::: "memory");
;     const int c = lane & 7;
; #pragma unroll
;     for (int j = 0; j < 4; ++j) { const int n = (lane >> 3) + 8 * j; const LAS float* s = scr + (8 * c) * 33 + n;
;         u32x4 o; o.x = pk2(s[0 * 33], s[1 * 33]); o.y = pk2(s[2 * 33], s[3 * 33]); o.z = pk2(s[4 * 33], s[5 * 33]); o.w = pk2(s[6 * 33], s[7 * 33]);
;         int cdst = n0 + n;
;         if (QKPERM && cdst >= 5 * WA && cdst < 7 * WA) cdst = (cdst & ~0x30) | ((cdst & 0x10) << 1) | ((cdst & 0x20) >> 1);
;         *(u32x4*)(WT + (size_t)(row_off + cdst) * K + k0 + 8 * c) = o; }
;     asm volatile("s_waitcnt lgkmcnt(0)" ::: "memory");
; __device__ __forceinline__ void phase_wconv_in(const Params& p, LAS unsigned char* lds, int gw, int NGW) {
;     ...
;     for (int it = gw; it < I_IN; it += NGW) transpose_item<true, false>(p.w_in, D_MODEL, IN_COLS, (bf16*)(p.ws + WS_WINT), 0, scr, it, lane);
	global_load_dword v108, v[52:53], off nt
	global_load_dword v30, v[54:55], off nt
	global_load_dword v31, v[56:57], off nt
	global_load_dword v32, v[58:59], off nt
	global_load_dword v33, v[60:61], off nt
	global_load_dword v34, v[62:63], off nt
	global_load_dword v35, v[64:65], off nt
	global_load_dword v44, v[66:67], off nt
	global_load_dword v45, v[68:69], off nt
	global_load_dword v46, v[70:71], off nt
	global_load_dword v47, v[72:73], off nt
	global_load_dword v48, v[74:75], off nt
	global_load_dword v49, v[76:77], off nt
	global_load_dword v50, v[78:79], off nt
	global_load_dword v51, v[80:81], off nt
	global_load_dword v52, v[82:83], off nt
	global_load_dword v53, v[84:85], off nt
	global_load_dword v54, v[22:23], off nt
	v_add_u32_e32 v87, s6, v5
	v_lshrrev_b32_e32 v90, 1, v87
	v_add_u32_e32 v91, 8, v87
	v_add_u32_e32 v93, 16, v87
	v_add_u32_e32 v95, 24, v87
	v_add_u32_e32 v88, 0xffffec00, v87
	v_and_b32_e32 v89, 0x1fcf, v87
	v_and_b32_e32 v22, 16, v90
	v_lshrrev_b32_e32 v25, 1, v91
	v_lshrrev_b32_e32 v27, 1, v93
	v_lshrrev_b32_e32 v29, 1, v95
	v_add_u32_e32 v92, 0xffffec08, v87
	v_add_u32_e32 v94, 0xffffec10, v87
	v_add_u32_e32 v23, 0xffffec18, v87
	v_and_b32_e32 v24, 0x1fcf, v91
	v_and_b32_e32 v26, 0x1fcf, v93
	v_and_b32_e32 v28, 0x1fcf, v95
	v_or3_b32 v22, v89, v7, v22
	v_and_b32_e32 v25, 16, v25
	v_and_b32_e32 v27, 16, v27
	v_and_b32_e32 v29, 16, v29
	v_cmp_gt_u32_e32 vcc, s11, v88
	v_or3_b32 v24, v24, v8, v25
	v_or3_b32 v25, v26, v9, v27
	v_cndmask_b32_e32 v22, v87, v22, vcc
	v_cmp_gt_u32_e32 vcc, s11, v92
	v_cmp_gt_u32_e64 s[4:5], s11, v94
	v_or3_b32 v27, v28, v10, v29
	v_cmp_gt_u32_e64 s[6:7], s11, v23
	v_ashrrev_i32_e32 v23, 31, v22
	v_cndmask_b32_e32 v24, v91, v24, vcc
	v_cndmask_b32_e64 v26, v93, v25, s[4:5]
	v_cndmask_b32_e64 v28, v95, v27, s[6:7]
	v_lshlrev_b64 v[22:23], 12, v[22:23]
	v_ashrrev_i32_e32 v25, 31, v24
	v_ashrrev_i32_e32 v27, 31, v26
	v_ashrrev_i32_e32 v29, 31, v28
	s_waitcnt vmcnt(30)
	ds_write2_b32 v11, v19, v86 offset1:66
	s_waitcnt vmcnt(28)
	ds_write2_b32 v11, v96, v97 offset0:132 offset1:198
	s_waitcnt vmcnt(26)
	ds_write2_b32 v12, v98, v99 offset0:8 offset1:74
	s_waitcnt vmcnt(24)
	ds_write2_b32 v12, v100, v101 offset0:140 offset1:206
	s_waitcnt vmcnt(22)
	ds_write2_b32 v13, v102, v103 offset0:16 offset1:82
	s_waitcnt vmcnt(20)
	ds_write2_b32 v13, v104, v105 offset0:148 offset1:214
	s_waitcnt vmcnt(18)
	ds_write2_b32 v14, v106, v107 offset0:24 offset1:90
	s_waitcnt vmcnt(16)
	ds_write2_b32 v14, v108, v30 offset0:156 offset1:222
	s_waitcnt vmcnt(14)
	ds_write2_b32 v15, v31, v32 offset0:32 offset1:98
	s_waitcnt vmcnt(12)
	ds_write2_b32 v15, v33, v34 offset0:164 offset1:230
	s_waitcnt vmcnt(10)
	ds_write2_b32 v16, v35, v44 offset0:40 offset1:106
	s_waitcnt vmcnt(8)
	ds_write2_b32 v16, v45, v46 offset0:172 offset1:238
	s_waitcnt vmcnt(6)
	ds_write2_b32 v17, v47, v48 offset0:48 offset1:114
	s_waitcnt vmcnt(4)
	ds_write2_b32 v17, v49, v50 offset0:180 offset1:246
	s_waitcnt vmcnt(2)
	ds_write2_b32 v18, v51, v52 offset0:56 offset1:122
	s_waitcnt vmcnt(0)
	ds_write2_b32 v18, v53, v54 offset0:188 offset1:254
	v_lshl_add_u64 v[36:37], v[20:21], 0, v[22:23]
	v_lshlrev_b64 v[22:23], 12, v[24:25]
	v_lshlrev_b64 v[24:25], 12, v[26:27]
	v_lshlrev_b64 v[26:27], 12, v[28:29]
	s_waitcnt lgkmcnt(0)
	v_lshl_add_u64 v[40:41], v[20:21], 0, v[24:25]
	v_lshl_add_u64 v[42:43], v[20:21], 0, v[26:27]
	ds_read2_b32 v[24:25], v6 offset0:33 offset1:41
	ds_read2_b32 v[26:27], v6 offset1:8
	ds_read2_b32 v[28:29], v6 offset0:66 offset1:74
	ds_read2_b32 v[30:31], v6 offset0:99 offset1:107
	ds_read2_b32 v[32:33], v6 offset0:132 offset1:140
	ds_read2_b32 v[34:35], v6 offset0:165 offset1:173
	ds_read2_b32 v[44:45], v6 offset0:198 offset1:206
	ds_read2_b32 v[46:47], v6 offset0:231 offset1:239
	ds_read2_b32 v[48:49], v6 offset0:16 offset1:24
	ds_read2_b32 v[50:51], v6 offset0:49 offset1:57
	ds_read2_b32 v[52:53], v6 offset0:82 offset1:90
	ds_read2_b32 v[54:55], v6 offset0:115 offset1:123
	ds_read2_b32 v[56:57], v6 offset0:148 offset1:156
	ds_read2_b32 v[58:59], v6 offset0:181 offset1:189
	ds_read2_b32 v[60:61], v6 offset0:214 offset1:222
	ds_read2_b32 v[62:63], v6 offset0:247 offset1:255
	v_lshl_add_u64 v[38:39], v[20:21], 0, v[22:23]
	s_waitcnt lgkmcnt(14)
	v_cvt_pk_bf16_f32 v20, v26, v24
	s_waitcnt lgkmcnt(12)
	v_cvt_pk_bf16_f32 v21, v28, v30
	s_waitcnt lgkmcnt(10)
	v_cvt_pk_bf16_f32 v22, v32, v34
	s_waitcnt lgkmcnt(8)
	v_cvt_pk_bf16_f32 v23, v44, v46
	v_cvt_pk_bf16_f32 v24, v27, v25
	v_cvt_pk_bf16_f32 v25, v29, v31
	v_cvt_pk_bf16_f32 v26, v33, v35
	v_cvt_pk_bf16_f32 v27, v45, v47
	s_waitcnt lgkmcnt(6)
	v_cvt_pk_bf16_f32 v28, v48, v50
	s_waitcnt lgkmcnt(4)
	v_cvt_pk_bf16_f32 v29, v52, v54
	s_waitcnt lgkmcnt(2)
	v_cvt_pk_bf16_f32 v30, v56, v58
	s_waitcnt lgkmcnt(0)
	v_cvt_pk_bf16_f32 v31, v60, v62
	v_cvt_pk_bf16_f32 v32, v49, v51
	v_cvt_pk_bf16_f32 v33, v53, v55
	v_cvt_pk_bf16_f32 v34, v57, v59
	v_cvt_pk_bf16_f32 v35, v61, v63
	global_store_dwordx4 v[36:37], v[20:23], off
	global_store_dwordx4 v[38:39], v[24:27], off
	global_store_dwordx4 v[40:41], v[28:31], off
	global_store_dwordx4 v[42:43], v[32:35], off
	s_waitcnt lgkmcnt(0)
	s_add_i32 s12, s12, s97
	s_add_i32 s8, s8, s9
	s_cmp_lt_i32 s12, s98
	s_cbranch_scc1 .LBB0_45
